# v24 + grid-barrier poll s_sleep 32 -> 4
# baseline (speedup 1.0000x reference)
; DI void gbar(unsigned* ctr, unsigned& gen, unsigned G) {
;     ...
;         while (__hip_atomic_load(ctr, __ATOMIC_RELAXED, __HIP_MEMORY_SCOPE_AGENT) < gen * G) __builtin_amdgcn_s_sleep(32);
.LBB0_1202:
	s_sleep 4
	global_load_dword v2, v1, s[62:63] sc1
	s_waitcnt vmcnt(0)
	v_cmp_gt_u32_e32 vcc, s86, v2
	s_cbranch_vccnz .LBB0_1202

; DI void gbar(unsigned* ctr, unsigned& gen, unsigned G) {
;     asm volatile("s_waitcnt vmcnt(0)" ::: "memory");
;     __syncthreads();
;     gen += 1;
;     if (threadIdx.x == 0) {
;         __builtin_amdgcn_fence(__ATOMIC_RELEASE, "agent");
;         asm volatile("s_waitcnt vmcnt(0)" ::: "memory");
;         __hip_atomic_fetch_add(ctr, 1u, __ATOMIC_RELAXED, __HIP_MEMORY_SCOPE_AGENT);
;         while (__hip_atomic_load(ctr, __ATOMIC_RELAXED, __HIP_MEMORY_SCOPE_AGENT) < gen * G) __builtin_amdgcn_s_sleep(32);
;         __builtin_amdgcn_fence(__ATOMIC_ACQUIRE, "agent");
;         asm volatile("s_waitcnt vmcnt(0)" ::: "memory");
;     }
;     __syncthreads();
.LBB0_1242:
	s_sleep 4
	global_load_dword v3, v1, s[62:63] sc1
	s_waitcnt vmcnt(0)
	v_cmp_ge_u32_e32 vcc, v3, v2
	s_or_b64 s[6:7], vcc, s[6:7]
	s_andn2_b64 exec, exec, s[6:7]
	s_cbranch_execnz .LBB0_1242

; DI void gbar(unsigned* ctr, unsigned& gen, unsigned G) {
;     asm volatile("s_waitcnt vmcnt(0)" ::: "memory");
;     __syncthreads();
;     gen += 1;
;     if (threadIdx.x == 0) {
;         __builtin_amdgcn_fence(__ATOMIC_RELEASE, "agent");
;         asm volatile("s_waitcnt vmcnt(0)" ::: "memory");
;         __hip_atomic_fetch_add(ctr, 1u, __ATOMIC_RELAXED, __HIP_MEMORY_SCOPE_AGENT);
;         while (__hip_atomic_load(ctr, __ATOMIC_RELAXED, __HIP_MEMORY_SCOPE_AGENT) < gen * G) __builtin_amdgcn_s_sleep(32);
;         __builtin_amdgcn_fence(__ATOMIC_ACQUIRE, "agent");
;         asm volatile("s_waitcnt vmcnt(0)" ::: "memory");
;     }
;     __syncthreads();
.LBB0_1397:
	s_sleep 4
	global_load_dword v3, v1, s[62:63] sc1
	s_waitcnt vmcnt(0)
	v_cmp_ge_u32_e32 vcc, v3, v2
	s_or_b64 s[8:9], vcc, s[8:9]
	s_andn2_b64 exec, exec, s[8:9]
	s_cbranch_execnz .LBB0_1397
